# P0a weight transposes: both 16-load trips of an item in flight before the LDS writes
# speedup vs baseline: 1.0037x; 1.0037x over previous
.LBB0_41:
	s_lshl_b32 s14, s6, 1
	s_lshl_b32 s15, s7, 1
	v_or_b32_e32 v4, s15, v20
	s_add_i32 s16, s14, 4
	s_add_i32 s17, s15, 4
	v_mov_b32_e32 v29, v5
	s_add_i32 s19, s15, 8
	v_lshlrev_b64 v[42:43], 12, v[4:5]
	v_or_b32_e32 v28, s16, v3
	v_or_b32_e32 v4, s17, v20
	v_mov_b32_e32 v27, v5
	v_or_b32_e32 v26, s14, v3
	s_add_i32 s21, s15, 12
	v_lshlrev_b64 v[28:29], 12, v[28:29]
	v_lshlrev_b64 v[44:45], 12, v[4:5]
	v_or_b32_e32 v4, s19, v20
	s_add_i32 s18, s14, 8
	s_add_i32 s20, s14, 12
	s_add_i32 s23, s15, 16
	v_lshlrev_b64 v[26:27], 12, v[26:27]
	v_lshl_add_u64 v[42:43], v[18:19], 0, v[42:43]
	v_lshl_add_u64 v[28:29], v[18:19], 0, v[28:29]
	v_lshlrev_b64 v[46:47], 12, v[4:5]
	v_or_b32_e32 v4, s21, v20
	v_mov_b32_e32 v31, v5
	v_mov_b32_e32 v33, v5
	s_add_i32 s25, s15, 20
	v_or_b32_e32 v30, s18, v3
	v_or_b32_e32 v32, s20, v3
	v_lshl_add_u64 v[26:27], v[18:19], 0, v[26:27]
	v_lshl_add_u64 v[44:45], v[18:19], 0, v[44:45]
	global_load_dword v17, v[42:43], off
	global_load_dword v25, v[26:27], off
	global_load_dword v58, v[44:45], off
	global_load_dword v59, v[28:29], off
	v_lshlrev_b64 v[28:29], 12, v[4:5]
	v_or_b32_e32 v4, s23, v20
	s_add_i32 s22, s14, 16
	s_add_i32 s24, s14, 20
	s_add_i32 s27, s15, 24
	v_lshlrev_b64 v[30:31], 12, v[30:31]
	v_lshlrev_b64 v[32:33], 12, v[32:33]
	v_lshl_add_u64 v[26:27], v[18:19], 0, v[46:47]
	v_lshl_add_u64 v[28:29], v[18:19], 0, v[28:29]
	v_lshlrev_b64 v[42:43], 12, v[4:5]
	v_or_b32_e32 v4, s25, v20
	v_mov_b32_e32 v35, v5
	v_mov_b32_e32 v37, v5
	s_add_i32 s26, s14, 24
	s_add_i32 s28, s14, 28
	s_add_i32 s29, s15, 28
	v_or_b32_e32 v34, s22, v3
	v_or_b32_e32 v36, s24, v3
	v_lshl_add_u64 v[30:31], v[18:19], 0, v[30:31]
	v_lshl_add_u64 v[32:33], v[18:19], 0, v[32:33]
	global_load_dword v60, v[26:27], off
	global_load_dword v61, v[30:31], off
	global_load_dword v62, v[28:29], off
	global_load_dword v63, v[32:33], off
	v_lshlrev_b64 v[28:29], 12, v[4:5]
	v_or_b32_e32 v4, s27, v20
	v_mov_b32_e32 v39, v5
	v_mov_b32_e32 v41, v5
	v_or_b32_e32 v38, s26, v3
	v_or_b32_e32 v40, s28, v3
	v_lshlrev_b64 v[34:35], 12, v[34:35]
	v_lshlrev_b64 v[36:37], 12, v[36:37]
	v_lshl_add_u64 v[26:27], v[18:19], 0, v[42:43]
	v_lshl_add_u64 v[28:29], v[18:19], 0, v[28:29]
	v_lshlrev_b64 v[30:31], 12, v[4:5]
	v_or_b32_e32 v4, s29, v20
	v_lshlrev_b64 v[38:39], 12, v[38:39]
	v_lshlrev_b64 v[40:41], 12, v[40:41]
	v_lshl_add_u64 v[34:35], v[18:19], 0, v[34:35]
	v_lshl_add_u64 v[36:37], v[18:19], 0, v[36:37]
	global_load_dword v64, v[26:27], off
	global_load_dword v65, v[34:35], off
	global_load_dword v66, v[28:29], off
	global_load_dword v67, v[36:37], off
	v_lshl_add_u64 v[26:27], v[18:19], 0, v[30:31]
	v_lshlrev_b64 v[28:29], 12, v[4:5]
	v_lshl_add_u64 v[38:39], v[18:19], 0, v[38:39]
	v_lshl_add_u64 v[40:41], v[18:19], 0, v[40:41]
	v_lshl_add_u64 v[28:29], v[18:19], 0, v[28:29]
	global_load_dword v4, v[26:27], off
	global_load_dword v68, v[38:39], off
	global_load_dword v69, v[28:29], off
	global_load_dword v70, v[40:41], off
	v_or_b32_e32 v28, s14, v1
	v_or_b32_e32 v26, s15, v2
	s_add_i32 s7, s7, 16
	s_add_i32 s6, s6, 16
	s_add_i32 s13, s13, -16
	v_mad_u64_u32 v[26:27], s[14:15], v26, s12, v[6:7]
	v_mad_u64_u32 v[28:29], s[14:15], v28, s12, v[6:7]
	v_or_b32_e32 v27, s16, v1
	v_or_b32_e32 v29, s17, v2
	v_or_b32_e32 v36, s18, v1
	v_or_b32_e32 v34, s19, v2
	v_or_b32_e32 v40, s20, v1
	v_or_b32_e32 v38, s21, v2
	v_or_b32_e32 v44, s22, v1
	v_or_b32_e32 v42, s23, v2
	v_or_b32_e32 v48, s24, v1
	v_or_b32_e32 v46, s25, v2
	v_or_b32_e32 v52, s26, v1
	v_or_b32_e32 v50, s27, v2
	v_or_b32_e32 v56, s28, v1
	v_or_b32_e32 v54, s29, v2
	s_cmp_lg_u32 s13, 0
	v_mad_u64_u32 v[30:31], s[14:15], v29, s12, v[6:7]
	v_mad_u64_u32 v[32:33], s[14:15], v27, s12, v[6:7]
	v_mad_u64_u32 v[34:35], s[14:15], v34, s12, v[6:7]
	v_mad_u64_u32 v[36:37], s[14:15], v36, s12, v[6:7]
	v_mad_u64_u32 v[38:39], s[14:15], v38, s12, v[6:7]
	v_mad_u64_u32 v[40:41], s[14:15], v40, s12, v[6:7]
	v_mad_u64_u32 v[42:43], s[14:15], v42, s12, v[6:7]
	v_mad_u64_u32 v[44:45], s[14:15], v44, s12, v[6:7]
	v_mad_u64_u32 v[46:47], s[14:15], v46, s12, v[6:7]
	v_mad_u64_u32 v[48:49], s[14:15], v48, s12, v[6:7]
	v_mad_u64_u32 v[50:51], s[14:15], v50, s12, v[6:7]
	v_mad_u64_u32 v[52:53], s[14:15], v52, s12, v[6:7]
	v_mad_u64_u32 v[54:55], s[14:15], v54, s12, v[6:7]
	v_mad_u64_u32 v[56:57], s[14:15], v56, s12, v[6:7]
	v_mov_b32_e32 v105, v5
	s_lshl_b32 s14, s6, 1
	s_lshl_b32 s15, s7, 1
	v_or_b32_e32 v104, s15, v20
	s_add_i32 s16, s14, 4
	s_add_i32 s17, s15, 4
	v_mov_b32_e32 v129, v5
	s_add_i32 s19, s15, 8
	v_lshlrev_b64 v[142:143], 12, v[104:105]
	v_or_b32_e32 v128, s16, v3
	v_or_b32_e32 v104, s17, v20
	v_mov_b32_e32 v127, v5
	v_or_b32_e32 v126, s14, v3
	s_add_i32 s21, s15, 12
	v_lshlrev_b64 v[128:129], 12, v[128:129]
	v_lshlrev_b64 v[144:145], 12, v[104:105]
	v_or_b32_e32 v104, s19, v20
	s_add_i32 s18, s14, 8
	s_add_i32 s20, s14, 12
	s_add_i32 s23, s15, 16
	v_lshlrev_b64 v[126:127], 12, v[126:127]
	v_lshl_add_u64 v[142:143], v[18:19], 0, v[142:143]
	v_lshl_add_u64 v[128:129], v[18:19], 0, v[128:129]
	v_lshlrev_b64 v[146:147], 12, v[104:105]
	v_or_b32_e32 v104, s21, v20
	v_mov_b32_e32 v131, v5
	v_mov_b32_e32 v133, v5
	s_add_i32 s25, s15, 20
	v_or_b32_e32 v130, s18, v3
	v_or_b32_e32 v132, s20, v3
	v_lshl_add_u64 v[126:127], v[18:19], 0, v[126:127]
	v_lshl_add_u64 v[144:145], v[18:19], 0, v[144:145]
	global_load_dword v117, v[142:143], off
	global_load_dword v125, v[126:127], off
	global_load_dword v158, v[144:145], off
	global_load_dword v159, v[128:129], off
	v_lshlrev_b64 v[128:129], 12, v[104:105]
	v_or_b32_e32 v104, s23, v20
	s_add_i32 s22, s14, 16
	s_add_i32 s24, s14, 20
	s_add_i32 s27, s15, 24
	v_lshlrev_b64 v[130:131], 12, v[130:131]
	v_lshlrev_b64 v[132:133], 12, v[132:133]
	v_lshl_add_u64 v[126:127], v[18:19], 0, v[146:147]
	v_lshl_add_u64 v[128:129], v[18:19], 0, v[128:129]
	v_lshlrev_b64 v[142:143], 12, v[104:105]
	v_or_b32_e32 v104, s25, v20
	v_mov_b32_e32 v135, v5
	v_mov_b32_e32 v137, v5
	s_add_i32 s26, s14, 24
	s_add_i32 s28, s14, 28
	s_add_i32 s29, s15, 28
	v_or_b32_e32 v134, s22, v3
	v_or_b32_e32 v136, s24, v3
	v_lshl_add_u64 v[130:131], v[18:19], 0, v[130:131]
	v_lshl_add_u64 v[132:133], v[18:19], 0, v[132:133]
	global_load_dword v160, v[126:127], off
	global_load_dword v161, v[130:131], off
	global_load_dword v162, v[128:129], off
	global_load_dword v163, v[132:133], off
	v_lshlrev_b64 v[128:129], 12, v[104:105]
	v_or_b32_e32 v104, s27, v20
	v_mov_b32_e32 v139, v5
	v_mov_b32_e32 v141, v5
	v_or_b32_e32 v138, s26, v3
	v_or_b32_e32 v140, s28, v3
	v_lshlrev_b64 v[134:135], 12, v[134:135]
	v_lshlrev_b64 v[136:137], 12, v[136:137]
	v_lshl_add_u64 v[126:127], v[18:19], 0, v[142:143]
	v_lshl_add_u64 v[128:129], v[18:19], 0, v[128:129]
	v_lshlrev_b64 v[130:131], 12, v[104:105]
	v_or_b32_e32 v104, s29, v20
	v_lshlrev_b64 v[138:139], 12, v[138:139]
	v_lshlrev_b64 v[140:141], 12, v[140:141]
	v_lshl_add_u64 v[134:135], v[18:19], 0, v[134:135]
	v_lshl_add_u64 v[136:137], v[18:19], 0, v[136:137]
	global_load_dword v164, v[126:127], off
	global_load_dword v165, v[134:135], off
	global_load_dword v166, v[128:129], off
	global_load_dword v167, v[136:137], off
	v_lshl_add_u64 v[126:127], v[18:19], 0, v[130:131]
	v_lshlrev_b64 v[128:129], 12, v[104:105]
	v_lshl_add_u64 v[138:139], v[18:19], 0, v[138:139]
	v_lshl_add_u64 v[140:141], v[18:19], 0, v[140:141]
	v_lshl_add_u64 v[128:129], v[18:19], 0, v[128:129]
	global_load_dword v104, v[126:127], off
	global_load_dword v168, v[138:139], off
	global_load_dword v169, v[128:129], off
	global_load_dword v170, v[140:141], off
	v_or_b32_e32 v128, s14, v1
	v_or_b32_e32 v126, s15, v2
	s_add_i32 s7, s7, 16
	s_add_i32 s6, s6, 16
	s_add_i32 s13, s13, -16
	v_mad_u64_u32 v[126:127], s[14:15], v126, s12, v[6:7]
	v_mad_u64_u32 v[128:129], s[14:15], v128, s12, v[6:7]
	v_or_b32_e32 v127, s16, v1
	v_or_b32_e32 v129, s17, v2
	v_or_b32_e32 v136, s18, v1
	v_or_b32_e32 v134, s19, v2
	v_or_b32_e32 v140, s20, v1
	v_or_b32_e32 v138, s21, v2
	v_or_b32_e32 v144, s22, v1
	v_or_b32_e32 v142, s23, v2
	v_or_b32_e32 v148, s24, v1
	v_or_b32_e32 v146, s25, v2
	v_or_b32_e32 v152, s26, v1
	v_or_b32_e32 v150, s27, v2
	v_or_b32_e32 v156, s28, v1
	v_or_b32_e32 v154, s29, v2
	s_cmp_lg_u32 s13, 0
	v_mad_u64_u32 v[130:131], s[14:15], v129, s12, v[6:7]
	v_mad_u64_u32 v[132:133], s[14:15], v127, s12, v[6:7]
	v_mad_u64_u32 v[134:135], s[14:15], v134, s12, v[6:7]
	v_mad_u64_u32 v[136:137], s[14:15], v136, s12, v[6:7]
	v_mad_u64_u32 v[138:139], s[14:15], v138, s12, v[6:7]
	v_mad_u64_u32 v[140:141], s[14:15], v140, s12, v[6:7]
	v_mad_u64_u32 v[142:143], s[14:15], v142, s12, v[6:7]
	v_mad_u64_u32 v[144:145], s[14:15], v144, s12, v[6:7]
	v_mad_u64_u32 v[146:147], s[14:15], v146, s12, v[6:7]
	v_mad_u64_u32 v[148:149], s[14:15], v148, s12, v[6:7]
	v_mad_u64_u32 v[150:151], s[14:15], v150, s12, v[6:7]
	v_mad_u64_u32 v[152:153], s[14:15], v152, s12, v[6:7]
	v_mad_u64_u32 v[154:155], s[14:15], v154, s12, v[6:7]
	v_mad_u64_u32 v[156:157], s[14:15], v156, s12, v[6:7]
	s_waitcnt vmcnt(31)
	ds_write_b32 v26, v17
	s_waitcnt vmcnt(30)
	ds_write_b32 v28, v25
	s_waitcnt vmcnt(29)
	ds_write_b32 v30, v58
	s_waitcnt vmcnt(28)
	ds_write_b32 v32, v59
	s_waitcnt vmcnt(27)
	ds_write_b32 v34, v60
	s_waitcnt vmcnt(26)
	ds_write_b32 v36, v61
	s_waitcnt vmcnt(25)
	ds_write_b32 v38, v62
	s_waitcnt vmcnt(24)
	ds_write_b32 v40, v63
	s_waitcnt vmcnt(23)
	ds_write_b32 v42, v64
	s_waitcnt vmcnt(22)
	ds_write_b32 v44, v65
	s_waitcnt vmcnt(21)
	ds_write_b32 v46, v66
	s_waitcnt vmcnt(20)
	ds_write_b32 v48, v67
	s_waitcnt vmcnt(19)
	ds_write_b32 v50, v4
	s_waitcnt vmcnt(18)
	ds_write_b32 v52, v68
	s_waitcnt vmcnt(17)
	ds_write_b32 v54, v69
	s_waitcnt vmcnt(16)
	ds_write_b32 v56, v70
	s_waitcnt vmcnt(15)
	ds_write_b32 v126, v117
	s_waitcnt vmcnt(14)
	ds_write_b32 v128, v125
	s_waitcnt vmcnt(13)
	ds_write_b32 v130, v158
	s_waitcnt vmcnt(12)
	ds_write_b32 v132, v159
	s_waitcnt vmcnt(11)
	ds_write_b32 v134, v160
	s_waitcnt vmcnt(10)
	ds_write_b32 v136, v161
	s_waitcnt vmcnt(9)
	ds_write_b32 v138, v162
	s_waitcnt vmcnt(8)
	ds_write_b32 v140, v163
	s_waitcnt vmcnt(7)
	ds_write_b32 v142, v164
	s_waitcnt vmcnt(6)
	ds_write_b32 v144, v165
	s_waitcnt vmcnt(5)
	ds_write_b32 v146, v166
	s_waitcnt vmcnt(4)
	ds_write_b32 v148, v167
	s_waitcnt vmcnt(3)
	ds_write_b32 v150, v104
	s_waitcnt vmcnt(2)
	ds_write_b32 v152, v168
	s_waitcnt vmcnt(1)
	ds_write_b32 v154, v169
	s_waitcnt vmcnt(0)
	ds_write_b32 v156, v170
	s_waitcnt lgkmcnt(0)
	ds_read2_b32 v[18:19], v21 offset0:33 offset1:41
	ds_read2_b32 v[30:31], v21 offset1:8
	ds_read2_b32 v[32:33], v21 offset0:66 offset1:74
	ds_read2_b32 v[34:35], v21 offset0:99 offset1:107
	ds_read2_b32 v[36:37], v21 offset0:132 offset1:140
	ds_read2_b32 v[38:39], v21 offset0:165 offset1:173
	ds_read2_b32 v[40:41], v21 offset0:198 offset1:206
	ds_read2_b32 v[42:43], v21 offset0:231 offset1:239
	s_lshl_b32 s4, s4, 1
	v_or_b32_e32 v3, s8, v7
	v_lshl_add_u64 v[44:45], v[8:9], 0, s[4:5]
	v_lshlrev_b32_e32 v4, 11, v3
	s_waitcnt lgkmcnt(6)
	v_cvt_pk_bf16_f32 v26, v30, v18
	s_waitcnt lgkmcnt(4)
	v_cvt_pk_bf16_f32 v27, v32, v34
	s_waitcnt lgkmcnt(2)
	v_cvt_pk_bf16_f32 v28, v36, v38
	s_waitcnt lgkmcnt(0)
	v_cvt_pk_bf16_f32 v29, v40, v42
	v_lshl_add_u64 v[46:47], v[44:45], 0, v[4:5]
	global_store_dwordx4 v[46:47], v[26:29], off
	v_or_b32_e32 v3, s8, v22
	v_lshlrev_b32_e32 v4, 11, v3
	v_cvt_pk_bf16_f32 v26, v31, v19
	v_cvt_pk_bf16_f32 v27, v33, v35
	v_cvt_pk_bf16_f32 v28, v37, v39
	v_cvt_pk_bf16_f32 v29, v41, v43
	ds_read2_b32 v[30:31], v21 offset0:49 offset1:57
	ds_read2_b32 v[32:33], v21 offset0:16 offset1:24
	ds_read2_b32 v[34:35], v21 offset0:82 offset1:90
	ds_read2_b32 v[36:37], v21 offset0:115 offset1:123
	ds_read2_b32 v[38:39], v21 offset0:148 offset1:156
	ds_read2_b32 v[40:41], v21 offset0:181 offset1:189
	ds_read2_b32 v[42:43], v21 offset0:214 offset1:222
	ds_read2_b32 v[46:47], v21 offset0:247 offset1:255
	v_or_b32_e32 v3, s8, v23
	v_lshl_add_u64 v[18:19], v[44:45], 0, v[4:5]
	v_lshlrev_b32_e32 v4, 11, v3
	v_or_b32_e32 v3, s8, v24
	global_store_dwordx4 v[18:19], v[26:29], off
	v_lshl_add_u64 v[18:19], v[44:45], 0, v[4:5]
	v_lshlrev_b32_e32 v4, 11, v3
	s_waitcnt lgkmcnt(6)
	v_cvt_pk_bf16_f32 v26, v32, v30
	s_waitcnt lgkmcnt(4)
	v_cvt_pk_bf16_f32 v27, v34, v36
	s_waitcnt lgkmcnt(2)
	v_cvt_pk_bf16_f32 v28, v38, v40
	s_waitcnt lgkmcnt(0)
	v_cvt_pk_bf16_f32 v29, v42, v46
	global_store_dwordx4 v[18:19], v[26:29], off
	v_lshl_add_u64 v[18:19], v[44:45], 0, v[4:5]
	s_mov_b64 s[6:7], 0
	v_cvt_pk_bf16_f32 v26, v33, v31
	v_cvt_pk_bf16_f32 v27, v35, v37
	v_cvt_pk_bf16_f32 v28, v39, v41
	v_cvt_pk_bf16_f32 v29, v43, v47
	global_store_dwordx4 v[18:19], v[26:29], off
	s_waitcnt lgkmcnt(0)

.LBB0_45:
	s_lshl_b32 s13, s6, 1
	s_lshl_b32 s14, s7, 1
	v_or_b32_e32 v4, s14, v20
	s_add_i32 s16, s13, 4
	s_add_i32 s17, s14, 4
	v_mov_b32_e32 v29, v5
	s_add_i32 s19, s14, 8
	v_lshlrev_b64 v[42:43], 12, v[4:5]
	v_or_b32_e32 v28, s16, v3
	v_or_b32_e32 v4, s17, v20
	v_mov_b32_e32 v27, v5
	v_or_b32_e32 v26, s13, v3
	s_add_i32 s21, s14, 12
	v_lshlrev_b64 v[28:29], 12, v[28:29]
	v_lshlrev_b64 v[44:45], 12, v[4:5]
	v_or_b32_e32 v4, s19, v20
	s_add_i32 s18, s13, 8
	s_add_i32 s20, s13, 12
	s_add_i32 s23, s14, 16
	v_lshlrev_b64 v[26:27], 12, v[26:27]
	v_lshl_add_u64 v[42:43], v[18:19], 0, v[42:43]
	v_lshl_add_u64 v[28:29], v[18:19], 0, v[28:29]
	v_lshlrev_b64 v[46:47], 12, v[4:5]
	v_or_b32_e32 v4, s21, v20
	v_mov_b32_e32 v31, v5
	v_mov_b32_e32 v33, v5
	s_add_i32 s25, s14, 20
	v_or_b32_e32 v30, s18, v3
	v_or_b32_e32 v32, s20, v3
	v_lshl_add_u64 v[26:27], v[18:19], 0, v[26:27]
	v_lshl_add_u64 v[44:45], v[18:19], 0, v[44:45]
	global_load_dword v17, v[42:43], off
	global_load_dword v25, v[26:27], off
	global_load_dword v58, v[44:45], off
	global_load_dword v59, v[28:29], off
	v_lshlrev_b64 v[28:29], 12, v[4:5]
	v_or_b32_e32 v4, s23, v20
	s_add_i32 s22, s13, 16
	s_add_i32 s24, s13, 20
	s_add_i32 s27, s14, 24
	v_lshlrev_b64 v[30:31], 12, v[30:31]
	v_lshlrev_b64 v[32:33], 12, v[32:33]
	v_lshl_add_u64 v[26:27], v[18:19], 0, v[46:47]
	v_lshl_add_u64 v[28:29], v[18:19], 0, v[28:29]
	v_lshlrev_b64 v[42:43], 12, v[4:5]
	v_or_b32_e32 v4, s25, v20
	v_mov_b32_e32 v35, v5
	v_mov_b32_e32 v37, v5
	s_add_i32 s26, s13, 24
	s_add_i32 s28, s13, 28
	s_add_i32 s29, s14, 28
	v_or_b32_e32 v34, s22, v3
	v_or_b32_e32 v36, s24, v3
	v_lshl_add_u64 v[30:31], v[18:19], 0, v[30:31]
	v_lshl_add_u64 v[32:33], v[18:19], 0, v[32:33]
	global_load_dword v60, v[26:27], off
	global_load_dword v61, v[30:31], off
	global_load_dword v62, v[28:29], off
	global_load_dword v63, v[32:33], off
	v_lshlrev_b64 v[28:29], 12, v[4:5]
	v_or_b32_e32 v4, s27, v20
	v_mov_b32_e32 v39, v5
	v_mov_b32_e32 v41, v5
	v_or_b32_e32 v38, s26, v3
	v_or_b32_e32 v40, s28, v3
	v_lshlrev_b64 v[34:35], 12, v[34:35]
	v_lshlrev_b64 v[36:37], 12, v[36:37]
	v_lshl_add_u64 v[26:27], v[18:19], 0, v[42:43]
	v_lshl_add_u64 v[28:29], v[18:19], 0, v[28:29]
	v_lshlrev_b64 v[30:31], 12, v[4:5]
	v_or_b32_e32 v4, s29, v20
	v_lshlrev_b64 v[38:39], 12, v[38:39]
	v_lshlrev_b64 v[40:41], 12, v[40:41]
	v_lshl_add_u64 v[34:35], v[18:19], 0, v[34:35]
	v_lshl_add_u64 v[36:37], v[18:19], 0, v[36:37]
	global_load_dword v64, v[26:27], off
	global_load_dword v65, v[34:35], off
	global_load_dword v66, v[28:29], off
	global_load_dword v67, v[36:37], off
	v_lshl_add_u64 v[26:27], v[18:19], 0, v[30:31]
	v_lshlrev_b64 v[28:29], 12, v[4:5]
	v_lshl_add_u64 v[38:39], v[18:19], 0, v[38:39]
	v_lshl_add_u64 v[40:41], v[18:19], 0, v[40:41]
	v_lshl_add_u64 v[28:29], v[18:19], 0, v[28:29]
	global_load_dword v4, v[26:27], off
	global_load_dword v68, v[38:39], off
	global_load_dword v69, v[28:29], off
	global_load_dword v70, v[40:41], off
	v_or_b32_e32 v28, s13, v1
	v_or_b32_e32 v26, s14, v2
	s_add_i32 s7, s7, 16
	s_add_i32 s6, s6, 16
	s_add_i32 s9, s9, -16
	v_mad_u64_u32 v[26:27], s[14:15], v26, s12, v[6:7]
	v_mad_u64_u32 v[28:29], s[14:15], v28, s12, v[6:7]
	v_or_b32_e32 v27, s16, v1
	v_or_b32_e32 v29, s17, v2
	v_or_b32_e32 v36, s18, v1
	v_or_b32_e32 v34, s19, v2
	v_or_b32_e32 v40, s20, v1
	v_or_b32_e32 v38, s21, v2
	v_or_b32_e32 v44, s22, v1
	v_or_b32_e32 v42, s23, v2
	v_or_b32_e32 v48, s24, v1
	v_or_b32_e32 v46, s25, v2
	v_or_b32_e32 v52, s26, v1
	v_or_b32_e32 v50, s27, v2
	v_or_b32_e32 v56, s28, v1
	v_or_b32_e32 v54, s29, v2
	s_cmp_lg_u32 s9, 0
	v_mad_u64_u32 v[30:31], s[14:15], v29, s12, v[6:7]
	v_mad_u64_u32 v[32:33], s[14:15], v27, s12, v[6:7]
	v_mad_u64_u32 v[34:35], s[14:15], v34, s12, v[6:7]
	v_mad_u64_u32 v[36:37], s[14:15], v36, s12, v[6:7]
	v_mad_u64_u32 v[38:39], s[14:15], v38, s12, v[6:7]
	v_mad_u64_u32 v[40:41], s[14:15], v40, s12, v[6:7]
	v_mad_u64_u32 v[42:43], s[14:15], v42, s12, v[6:7]
	v_mad_u64_u32 v[44:45], s[14:15], v44, s12, v[6:7]
	v_mad_u64_u32 v[46:47], s[14:15], v46, s12, v[6:7]
	v_mad_u64_u32 v[48:49], s[14:15], v48, s12, v[6:7]
	v_mad_u64_u32 v[50:51], s[14:15], v50, s12, v[6:7]
	v_mad_u64_u32 v[52:53], s[14:15], v52, s12, v[6:7]
	v_mad_u64_u32 v[54:55], s[14:15], v54, s12, v[6:7]
	v_mad_u64_u32 v[56:57], s[14:15], v56, s12, v[6:7]
	v_mov_b32_e32 v105, v5
	s_lshl_b32 s13, s6, 1
	s_lshl_b32 s14, s7, 1
	v_or_b32_e32 v104, s14, v20
	s_add_i32 s16, s13, 4
	s_add_i32 s17, s14, 4
	v_mov_b32_e32 v129, v5
	s_add_i32 s19, s14, 8
	v_lshlrev_b64 v[142:143], 12, v[104:105]
	v_or_b32_e32 v128, s16, v3
	v_or_b32_e32 v104, s17, v20
	v_mov_b32_e32 v127, v5
	v_or_b32_e32 v126, s13, v3
	s_add_i32 s21, s14, 12
	v_lshlrev_b64 v[128:129], 12, v[128:129]
	v_lshlrev_b64 v[144:145], 12, v[104:105]
	v_or_b32_e32 v104, s19, v20
	s_add_i32 s18, s13, 8
	s_add_i32 s20, s13, 12
	s_add_i32 s23, s14, 16
	v_lshlrev_b64 v[126:127], 12, v[126:127]
	v_lshl_add_u64 v[142:143], v[18:19], 0, v[142:143]
	v_lshl_add_u64 v[128:129], v[18:19], 0, v[128:129]
	v_lshlrev_b64 v[146:147], 12, v[104:105]
	v_or_b32_e32 v104, s21, v20
	v_mov_b32_e32 v131, v5
	v_mov_b32_e32 v133, v5
	s_add_i32 s25, s14, 20
	v_or_b32_e32 v130, s18, v3
	v_or_b32_e32 v132, s20, v3
	v_lshl_add_u64 v[126:127], v[18:19], 0, v[126:127]
	v_lshl_add_u64 v[144:145], v[18:19], 0, v[144:145]
	global_load_dword v117, v[142:143], off
	global_load_dword v125, v[126:127], off
	global_load_dword v158, v[144:145], off
	global_load_dword v159, v[128:129], off
	v_lshlrev_b64 v[128:129], 12, v[104:105]
	v_or_b32_e32 v104, s23, v20
	s_add_i32 s22, s13, 16
	s_add_i32 s24, s13, 20
	s_add_i32 s27, s14, 24
	v_lshlrev_b64 v[130:131], 12, v[130:131]
	v_lshlrev_b64 v[132:133], 12, v[132:133]
	v_lshl_add_u64 v[126:127], v[18:19], 0, v[146:147]
	v_lshl_add_u64 v[128:129], v[18:19], 0, v[128:129]
	v_lshlrev_b64 v[142:143], 12, v[104:105]
	v_or_b32_e32 v104, s25, v20
	v_mov_b32_e32 v135, v5
	v_mov_b32_e32 v137, v5
	s_add_i32 s26, s13, 24
	s_add_i32 s28, s13, 28
	s_add_i32 s29, s14, 28
	v_or_b32_e32 v134, s22, v3
	v_or_b32_e32 v136, s24, v3
	v_lshl_add_u64 v[130:131], v[18:19], 0, v[130:131]
	v_lshl_add_u64 v[132:133], v[18:19], 0, v[132:133]
	global_load_dword v160, v[126:127], off
	global_load_dword v161, v[130:131], off
	global_load_dword v162, v[128:129], off
	global_load_dword v163, v[132:133], off
	v_lshlrev_b64 v[128:129], 12, v[104:105]
	v_or_b32_e32 v104, s27, v20
	v_mov_b32_e32 v139, v5
	v_mov_b32_e32 v141, v5
	v_or_b32_e32 v138, s26, v3
	v_or_b32_e32 v140, s28, v3
	v_lshlrev_b64 v[134:135], 12, v[134:135]
	v_lshlrev_b64 v[136:137], 12, v[136:137]
	v_lshl_add_u64 v[126:127], v[18:19], 0, v[142:143]
	v_lshl_add_u64 v[128:129], v[18:19], 0, v[128:129]
	v_lshlrev_b64 v[130:131], 12, v[104:105]
	v_or_b32_e32 v104, s29, v20
	v_lshlrev_b64 v[138:139], 12, v[138:139]
	v_lshlrev_b64 v[140:141], 12, v[140:141]
	v_lshl_add_u64 v[134:135], v[18:19], 0, v[134:135]
	v_lshl_add_u64 v[136:137], v[18:19], 0, v[136:137]
	global_load_dword v164, v[126:127], off
	global_load_dword v165, v[134:135], off
	global_load_dword v166, v[128:129], off
	global_load_dword v167, v[136:137], off
	v_lshl_add_u64 v[126:127], v[18:19], 0, v[130:131]
	v_lshlrev_b64 v[128:129], 12, v[104:105]
	v_lshl_add_u64 v[138:139], v[18:19], 0, v[138:139]
	v_lshl_add_u64 v[140:141], v[18:19], 0, v[140:141]
	v_lshl_add_u64 v[128:129], v[18:19], 0, v[128:129]
	global_load_dword v104, v[126:127], off
	global_load_dword v168, v[138:139], off
	global_load_dword v169, v[128:129], off
	global_load_dword v170, v[140:141], off
	v_or_b32_e32 v128, s13, v1
	v_or_b32_e32 v126, s14, v2
	s_add_i32 s7, s7, 16
	s_add_i32 s6, s6, 16
	s_add_i32 s9, s9, -16
	v_mad_u64_u32 v[126:127], s[14:15], v126, s12, v[6:7]
	v_mad_u64_u32 v[128:129], s[14:15], v128, s12, v[6:7]
	v_or_b32_e32 v127, s16, v1
	v_or_b32_e32 v129, s17, v2
	v_or_b32_e32 v136, s18, v1
	v_or_b32_e32 v134, s19, v2
	v_or_b32_e32 v140, s20, v1
	v_or_b32_e32 v138, s21, v2
	v_or_b32_e32 v144, s22, v1
	v_or_b32_e32 v142, s23, v2
	v_or_b32_e32 v148, s24, v1
	v_or_b32_e32 v146, s25, v2
	v_or_b32_e32 v152, s26, v1
	v_or_b32_e32 v150, s27, v2
	v_or_b32_e32 v156, s28, v1
	v_or_b32_e32 v154, s29, v2
	s_cmp_lg_u32 s9, 0
	v_mad_u64_u32 v[130:131], s[14:15], v129, s12, v[6:7]
	v_mad_u64_u32 v[132:133], s[14:15], v127, s12, v[6:7]
	v_mad_u64_u32 v[134:135], s[14:15], v134, s12, v[6:7]
	v_mad_u64_u32 v[136:137], s[14:15], v136, s12, v[6:7]
	v_mad_u64_u32 v[138:139], s[14:15], v138, s12, v[6:7]
	v_mad_u64_u32 v[140:141], s[14:15], v140, s12, v[6:7]
	v_mad_u64_u32 v[142:143], s[14:15], v142, s12, v[6:7]
	v_mad_u64_u32 v[144:145], s[14:15], v144, s12, v[6:7]
	v_mad_u64_u32 v[146:147], s[14:15], v146, s12, v[6:7]
	v_mad_u64_u32 v[148:149], s[14:15], v148, s12, v[6:7]
	v_mad_u64_u32 v[150:151], s[14:15], v150, s12, v[6:7]
	v_mad_u64_u32 v[152:153], s[14:15], v152, s12, v[6:7]
	v_mad_u64_u32 v[154:155], s[14:15], v154, s12, v[6:7]
	v_mad_u64_u32 v[156:157], s[14:15], v156, s12, v[6:7]
	s_waitcnt vmcnt(31)
	ds_write_b32 v26, v17
	s_waitcnt vmcnt(30)
	ds_write_b32 v28, v25
	s_waitcnt vmcnt(29)
	ds_write_b32 v30, v58
	s_waitcnt vmcnt(28)
	ds_write_b32 v32, v59
	s_waitcnt vmcnt(27)
	ds_write_b32 v34, v60
	s_waitcnt vmcnt(26)
	ds_write_b32 v36, v61
	s_waitcnt vmcnt(25)
	ds_write_b32 v38, v62
	s_waitcnt vmcnt(24)
	ds_write_b32 v40, v63
	s_waitcnt vmcnt(23)
	ds_write_b32 v42, v64
	s_waitcnt vmcnt(22)
	ds_write_b32 v44, v65
	s_waitcnt vmcnt(21)
	ds_write_b32 v46, v66
	s_waitcnt vmcnt(20)
	ds_write_b32 v48, v67
	s_waitcnt vmcnt(19)
	ds_write_b32 v50, v4
	s_waitcnt vmcnt(18)
	ds_write_b32 v52, v68
	s_waitcnt vmcnt(17)
	ds_write_b32 v54, v69
	s_waitcnt vmcnt(16)
	ds_write_b32 v56, v70
	s_waitcnt vmcnt(15)
	ds_write_b32 v126, v117
	s_waitcnt vmcnt(14)
	ds_write_b32 v128, v125
	s_waitcnt vmcnt(13)
	ds_write_b32 v130, v158
	s_waitcnt vmcnt(12)
	ds_write_b32 v132, v159
	s_waitcnt vmcnt(11)
	ds_write_b32 v134, v160
	s_waitcnt vmcnt(10)
	ds_write_b32 v136, v161
	s_waitcnt vmcnt(9)
	ds_write_b32 v138, v162
	s_waitcnt vmcnt(8)
	ds_write_b32 v140, v163
	s_waitcnt vmcnt(7)
	ds_write_b32 v142, v164
	s_waitcnt vmcnt(6)
	ds_write_b32 v144, v165
	s_waitcnt vmcnt(5)
	ds_write_b32 v146, v166
	s_waitcnt vmcnt(4)
	ds_write_b32 v148, v167
	s_waitcnt vmcnt(3)
	ds_write_b32 v150, v104
	s_waitcnt vmcnt(2)
	ds_write_b32 v152, v168
	s_waitcnt vmcnt(1)
	ds_write_b32 v154, v169
	s_waitcnt vmcnt(0)
	ds_write_b32 v156, v170
	s_waitcnt lgkmcnt(0)
	ds_read2_b32 v[18:19], v21 offset0:33 offset1:41
	ds_read2_b32 v[30:31], v21 offset1:8
	ds_read2_b32 v[32:33], v21 offset0:66 offset1:74
	ds_read2_b32 v[34:35], v21 offset0:99 offset1:107
	ds_read2_b32 v[36:37], v21 offset0:132 offset1:140
	ds_read2_b32 v[38:39], v21 offset0:165 offset1:173
	ds_read2_b32 v[40:41], v21 offset0:198 offset1:206
	ds_read2_b32 v[42:43], v21 offset0:231 offset1:239
	s_lshl_b32 s4, s4, 1
	v_or_b32_e32 v3, s8, v7
	v_lshl_add_u64 v[44:45], v[10:11], 0, s[4:5]
	v_lshlrev_b32_e32 v4, 11, v3
	s_waitcnt lgkmcnt(6)
	v_cvt_pk_bf16_f32 v26, v30, v18
	s_waitcnt lgkmcnt(4)
	v_cvt_pk_bf16_f32 v27, v32, v34
	s_waitcnt lgkmcnt(2)
	v_cvt_pk_bf16_f32 v28, v36, v38
	s_waitcnt lgkmcnt(0)
	v_cvt_pk_bf16_f32 v29, v40, v42
	v_lshl_add_u64 v[46:47], v[44:45], 0, v[4:5]
	global_store_dwordx4 v[46:47], v[26:29], off
	v_or_b32_e32 v3, s8, v22
	v_lshlrev_b32_e32 v4, 11, v3
	v_cvt_pk_bf16_f32 v26, v31, v19
	v_cvt_pk_bf16_f32 v27, v33, v35
	v_cvt_pk_bf16_f32 v28, v37, v39
	v_cvt_pk_bf16_f32 v29, v41, v43
	ds_read2_b32 v[30:31], v21 offset0:49 offset1:57
	ds_read2_b32 v[32:33], v21 offset0:16 offset1:24
	ds_read2_b32 v[34:35], v21 offset0:82 offset1:90
	ds_read2_b32 v[36:37], v21 offset0:115 offset1:123
	ds_read2_b32 v[38:39], v21 offset0:148 offset1:156
	ds_read2_b32 v[40:41], v21 offset0:181 offset1:189
	ds_read2_b32 v[42:43], v21 offset0:214 offset1:222
	ds_read2_b32 v[46:47], v21 offset0:247 offset1:255
	v_or_b32_e32 v3, s8, v23
	v_lshl_add_u64 v[18:19], v[44:45], 0, v[4:5]
	v_lshlrev_b32_e32 v4, 11, v3
	v_or_b32_e32 v3, s8, v24
	global_store_dwordx4 v[18:19], v[26:29], off
	v_lshl_add_u64 v[18:19], v[44:45], 0, v[4:5]
	v_lshlrev_b32_e32 v4, 11, v3
	s_waitcnt lgkmcnt(6)
	v_cvt_pk_bf16_f32 v26, v32, v30
	s_waitcnt lgkmcnt(4)
	v_cvt_pk_bf16_f32 v27, v34, v36
	s_waitcnt lgkmcnt(2)
	v_cvt_pk_bf16_f32 v28, v38, v40
	s_waitcnt lgkmcnt(0)
	v_cvt_pk_bf16_f32 v29, v42, v46
	global_store_dwordx4 v[18:19], v[26:29], off
	v_lshl_add_u64 v[18:19], v[44:45], 0, v[4:5]
	s_nop 0
	v_cvt_pk_bf16_f32 v26, v33, v31
	v_cvt_pk_bf16_f32 v27, v35, v37
	v_cvt_pk_bf16_f32 v28, v39, v41
	v_cvt_pk_bf16_f32 v29, v43, v47
	global_store_dwordx4 v[18:19], v[26:29], off
	s_waitcnt lgkmcnt(0)

.LBB0_50:
	s_lshl_b32 s13, s4, 1
	s_lshl_b32 s14, s8, 1
	v_or_b32_e32 v4, s14, v20
	s_add_i32 s16, s13, 4
	s_add_i32 s17, s14, 4
	v_mov_b32_e32 v29, v5
	s_add_i32 s19, s14, 8
	v_lshlrev_b64 v[42:43], 12, v[4:5]
	v_or_b32_e32 v28, s16, v3
	v_or_b32_e32 v4, s17, v20
	v_mov_b32_e32 v27, v5
	v_or_b32_e32 v26, s13, v3
	s_add_i32 s21, s14, 12
	v_lshlrev_b64 v[28:29], 12, v[28:29]
	v_lshlrev_b64 v[44:45], 12, v[4:5]
	v_or_b32_e32 v4, s19, v20
	s_add_i32 s18, s13, 8
	s_add_i32 s20, s13, 12
	s_add_i32 s23, s14, 16
	v_lshlrev_b64 v[26:27], 12, v[26:27]
	v_lshl_add_u64 v[42:43], v[18:19], 0, v[42:43]
	v_lshl_add_u64 v[28:29], v[18:19], 0, v[28:29]
	v_lshlrev_b64 v[46:47], 12, v[4:5]
	v_or_b32_e32 v4, s21, v20
	v_mov_b32_e32 v31, v5
	v_mov_b32_e32 v33, v5
	s_add_i32 s25, s14, 20
	v_or_b32_e32 v30, s18, v3
	v_or_b32_e32 v32, s20, v3
	v_lshl_add_u64 v[26:27], v[18:19], 0, v[26:27]
	v_lshl_add_u64 v[44:45], v[18:19], 0, v[44:45]
	global_load_dword v17, v[42:43], off
	global_load_dword v25, v[26:27], off
	global_load_dword v58, v[44:45], off
	global_load_dword v59, v[28:29], off
	v_lshlrev_b64 v[28:29], 12, v[4:5]
	v_or_b32_e32 v4, s23, v20
	s_add_i32 s22, s13, 16
	s_add_i32 s24, s13, 20
	s_add_i32 s27, s14, 24
	v_lshlrev_b64 v[30:31], 12, v[30:31]
	v_lshlrev_b64 v[32:33], 12, v[32:33]
	v_lshl_add_u64 v[26:27], v[18:19], 0, v[46:47]
	v_lshl_add_u64 v[28:29], v[18:19], 0, v[28:29]
	v_lshlrev_b64 v[42:43], 12, v[4:5]
	v_or_b32_e32 v4, s25, v20
	v_mov_b32_e32 v35, v5
	v_mov_b32_e32 v37, v5
	s_add_i32 s26, s13, 24
	s_add_i32 s28, s13, 28
	s_add_i32 s29, s14, 28
	v_or_b32_e32 v34, s22, v3
	v_or_b32_e32 v36, s24, v3
	v_lshl_add_u64 v[30:31], v[18:19], 0, v[30:31]
	v_lshl_add_u64 v[32:33], v[18:19], 0, v[32:33]
	global_load_dword v60, v[26:27], off
	global_load_dword v61, v[30:31], off
	global_load_dword v62, v[28:29], off
	global_load_dword v63, v[32:33], off
	v_lshlrev_b64 v[28:29], 12, v[4:5]
	v_or_b32_e32 v4, s27, v20
	v_mov_b32_e32 v39, v5
	v_mov_b32_e32 v41, v5
	v_or_b32_e32 v38, s26, v3
	v_or_b32_e32 v40, s28, v3
	v_lshlrev_b64 v[34:35], 12, v[34:35]
	v_lshlrev_b64 v[36:37], 12, v[36:37]
	v_lshl_add_u64 v[26:27], v[18:19], 0, v[42:43]
	v_lshl_add_u64 v[28:29], v[18:19], 0, v[28:29]
	v_lshlrev_b64 v[30:31], 12, v[4:5]
	v_or_b32_e32 v4, s29, v20
	v_lshlrev_b64 v[38:39], 12, v[38:39]
	v_lshlrev_b64 v[40:41], 12, v[40:41]
	v_lshl_add_u64 v[34:35], v[18:19], 0, v[34:35]
	v_lshl_add_u64 v[36:37], v[18:19], 0, v[36:37]
	global_load_dword v64, v[26:27], off
	global_load_dword v65, v[34:35], off
	global_load_dword v66, v[28:29], off
	global_load_dword v67, v[36:37], off
	v_lshl_add_u64 v[26:27], v[18:19], 0, v[30:31]
	v_lshlrev_b64 v[28:29], 12, v[4:5]
	v_lshl_add_u64 v[38:39], v[18:19], 0, v[38:39]
	v_lshl_add_u64 v[40:41], v[18:19], 0, v[40:41]
	v_lshl_add_u64 v[28:29], v[18:19], 0, v[28:29]
	global_load_dword v4, v[26:27], off
	global_load_dword v68, v[38:39], off
	global_load_dword v69, v[28:29], off
	global_load_dword v70, v[40:41], off
	v_or_b32_e32 v28, s13, v1
	v_or_b32_e32 v26, s14, v2
	s_add_i32 s8, s8, 16
	s_add_i32 s4, s4, 16
	s_add_i32 s9, s9, -16
	v_mad_u64_u32 v[26:27], s[14:15], v26, s12, v[6:7]
	v_mad_u64_u32 v[28:29], s[14:15], v28, s12, v[6:7]
	v_or_b32_e32 v27, s16, v1
	v_or_b32_e32 v29, s17, v2
	v_or_b32_e32 v36, s18, v1
	v_or_b32_e32 v34, s19, v2
	v_or_b32_e32 v40, s20, v1
	v_or_b32_e32 v38, s21, v2
	v_or_b32_e32 v44, s22, v1
	v_or_b32_e32 v42, s23, v2
	v_or_b32_e32 v48, s24, v1
	v_or_b32_e32 v46, s25, v2
	v_or_b32_e32 v52, s26, v1
	v_or_b32_e32 v50, s27, v2
	v_or_b32_e32 v56, s28, v1
	v_or_b32_e32 v54, s29, v2
	s_cmp_lg_u32 s9, 0
	v_mad_u64_u32 v[30:31], s[14:15], v29, s12, v[6:7]
	v_mad_u64_u32 v[32:33], s[14:15], v27, s12, v[6:7]
	v_mad_u64_u32 v[34:35], s[14:15], v34, s12, v[6:7]
	v_mad_u64_u32 v[36:37], s[14:15], v36, s12, v[6:7]
	v_mad_u64_u32 v[38:39], s[14:15], v38, s12, v[6:7]
	v_mad_u64_u32 v[40:41], s[14:15], v40, s12, v[6:7]
	v_mad_u64_u32 v[42:43], s[14:15], v42, s12, v[6:7]
	v_mad_u64_u32 v[44:45], s[14:15], v44, s12, v[6:7]
	v_mad_u64_u32 v[46:47], s[14:15], v46, s12, v[6:7]
	v_mad_u64_u32 v[48:49], s[14:15], v48, s12, v[6:7]
	v_mad_u64_u32 v[50:51], s[14:15], v50, s12, v[6:7]
	v_mad_u64_u32 v[52:53], s[14:15], v52, s12, v[6:7]
	v_mad_u64_u32 v[54:55], s[14:15], v54, s12, v[6:7]
	v_mad_u64_u32 v[56:57], s[14:15], v56, s12, v[6:7]
	v_mov_b32_e32 v105, v5
	s_lshl_b32 s13, s4, 1
	s_lshl_b32 s14, s8, 1
	v_or_b32_e32 v104, s14, v20
	s_add_i32 s16, s13, 4
	s_add_i32 s17, s14, 4
	v_mov_b32_e32 v129, v5
	s_add_i32 s19, s14, 8
	v_lshlrev_b64 v[142:143], 12, v[104:105]
	v_or_b32_e32 v128, s16, v3
	v_or_b32_e32 v104, s17, v20
	v_mov_b32_e32 v127, v5
	v_or_b32_e32 v126, s13, v3
	s_add_i32 s21, s14, 12
	v_lshlrev_b64 v[128:129], 12, v[128:129]
	v_lshlrev_b64 v[144:145], 12, v[104:105]
	v_or_b32_e32 v104, s19, v20
	s_add_i32 s18, s13, 8
	s_add_i32 s20, s13, 12
	s_add_i32 s23, s14, 16
	v_lshlrev_b64 v[126:127], 12, v[126:127]
	v_lshl_add_u64 v[142:143], v[18:19], 0, v[142:143]
	v_lshl_add_u64 v[128:129], v[18:19], 0, v[128:129]
	v_lshlrev_b64 v[146:147], 12, v[104:105]
	v_or_b32_e32 v104, s21, v20
	v_mov_b32_e32 v131, v5
	v_mov_b32_e32 v133, v5
	s_add_i32 s25, s14, 20
	v_or_b32_e32 v130, s18, v3
	v_or_b32_e32 v132, s20, v3
	v_lshl_add_u64 v[126:127], v[18:19], 0, v[126:127]
	v_lshl_add_u64 v[144:145], v[18:19], 0, v[144:145]
	global_load_dword v117, v[142:143], off
	global_load_dword v125, v[126:127], off
	global_load_dword v158, v[144:145], off
	global_load_dword v159, v[128:129], off
	v_lshlrev_b64 v[128:129], 12, v[104:105]
	v_or_b32_e32 v104, s23, v20
	s_add_i32 s22, s13, 16
	s_add_i32 s24, s13, 20
	s_add_i32 s27, s14, 24
	v_lshlrev_b64 v[130:131], 12, v[130:131]
	v_lshlrev_b64 v[132:133], 12, v[132:133]
	v_lshl_add_u64 v[126:127], v[18:19], 0, v[146:147]
	v_lshl_add_u64 v[128:129], v[18:19], 0, v[128:129]
	v_lshlrev_b64 v[142:143], 12, v[104:105]
	v_or_b32_e32 v104, s25, v20
	v_mov_b32_e32 v135, v5
	v_mov_b32_e32 v137, v5
	s_add_i32 s26, s13, 24
	s_add_i32 s28, s13, 28
	s_add_i32 s29, s14, 28
	v_or_b32_e32 v134, s22, v3
	v_or_b32_e32 v136, s24, v3
	v_lshl_add_u64 v[130:131], v[18:19], 0, v[130:131]
	v_lshl_add_u64 v[132:133], v[18:19], 0, v[132:133]
	global_load_dword v160, v[126:127], off
	global_load_dword v161, v[130:131], off
	global_load_dword v162, v[128:129], off
	global_load_dword v163, v[132:133], off
	v_lshlrev_b64 v[128:129], 12, v[104:105]
	v_or_b32_e32 v104, s27, v20
	v_mov_b32_e32 v139, v5
	v_mov_b32_e32 v141, v5
	v_or_b32_e32 v138, s26, v3
	v_or_b32_e32 v140, s28, v3
	v_lshlrev_b64 v[134:135], 12, v[134:135]
	v_lshlrev_b64 v[136:137], 12, v[136:137]
	v_lshl_add_u64 v[126:127], v[18:19], 0, v[142:143]
	v_lshl_add_u64 v[128:129], v[18:19], 0, v[128:129]
	v_lshlrev_b64 v[130:131], 12, v[104:105]
	v_or_b32_e32 v104, s29, v20
	v_lshlrev_b64 v[138:139], 12, v[138:139]
	v_lshlrev_b64 v[140:141], 12, v[140:141]
	v_lshl_add_u64 v[134:135], v[18:19], 0, v[134:135]
	v_lshl_add_u64 v[136:137], v[18:19], 0, v[136:137]
	global_load_dword v164, v[126:127], off
	global_load_dword v165, v[134:135], off
	global_load_dword v166, v[128:129], off
	global_load_dword v167, v[136:137], off
	v_lshl_add_u64 v[126:127], v[18:19], 0, v[130:131]
	v_lshlrev_b64 v[128:129], 12, v[104:105]
	v_lshl_add_u64 v[138:139], v[18:19], 0, v[138:139]
	v_lshl_add_u64 v[140:141], v[18:19], 0, v[140:141]
	v_lshl_add_u64 v[128:129], v[18:19], 0, v[128:129]
	global_load_dword v104, v[126:127], off
	global_load_dword v168, v[138:139], off
	global_load_dword v169, v[128:129], off
	global_load_dword v170, v[140:141], off
	v_or_b32_e32 v128, s13, v1
	v_or_b32_e32 v126, s14, v2
	s_add_i32 s8, s8, 16
	s_add_i32 s4, s4, 16
	s_add_i32 s9, s9, -16
	v_mad_u64_u32 v[126:127], s[14:15], v126, s12, v[6:7]
	v_mad_u64_u32 v[128:129], s[14:15], v128, s12, v[6:7]
	v_or_b32_e32 v127, s16, v1
	v_or_b32_e32 v129, s17, v2
	v_or_b32_e32 v136, s18, v1
	v_or_b32_e32 v134, s19, v2
	v_or_b32_e32 v140, s20, v1
	v_or_b32_e32 v138, s21, v2
	v_or_b32_e32 v144, s22, v1
	v_or_b32_e32 v142, s23, v2
	v_or_b32_e32 v148, s24, v1
	v_or_b32_e32 v146, s25, v2
	v_or_b32_e32 v152, s26, v1
	v_or_b32_e32 v150, s27, v2
	v_or_b32_e32 v156, s28, v1
	v_or_b32_e32 v154, s29, v2
	s_cmp_lg_u32 s9, 0
	v_mad_u64_u32 v[130:131], s[14:15], v129, s12, v[6:7]
	v_mad_u64_u32 v[132:133], s[14:15], v127, s12, v[6:7]
	v_mad_u64_u32 v[134:135], s[14:15], v134, s12, v[6:7]
	v_mad_u64_u32 v[136:137], s[14:15], v136, s12, v[6:7]
	v_mad_u64_u32 v[138:139], s[14:15], v138, s12, v[6:7]
	v_mad_u64_u32 v[140:141], s[14:15], v140, s12, v[6:7]
	v_mad_u64_u32 v[142:143], s[14:15], v142, s12, v[6:7]
	v_mad_u64_u32 v[144:145], s[14:15], v144, s12, v[6:7]
	v_mad_u64_u32 v[146:147], s[14:15], v146, s12, v[6:7]
	v_mad_u64_u32 v[148:149], s[14:15], v148, s12, v[6:7]
	v_mad_u64_u32 v[150:151], s[14:15], v150, s12, v[6:7]
	v_mad_u64_u32 v[152:153], s[14:15], v152, s12, v[6:7]
	v_mad_u64_u32 v[154:155], s[14:15], v154, s12, v[6:7]
	v_mad_u64_u32 v[156:157], s[14:15], v156, s12, v[6:7]
	s_waitcnt vmcnt(31)
	ds_write_b32 v26, v17
	s_waitcnt vmcnt(30)
	ds_write_b32 v28, v25
	s_waitcnt vmcnt(29)
	ds_write_b32 v30, v58
	s_waitcnt vmcnt(28)
	ds_write_b32 v32, v59
	s_waitcnt vmcnt(27)
	ds_write_b32 v34, v60
	s_waitcnt vmcnt(26)
	ds_write_b32 v36, v61
	s_waitcnt vmcnt(25)
	ds_write_b32 v38, v62
	s_waitcnt vmcnt(24)
	ds_write_b32 v40, v63
	s_waitcnt vmcnt(23)
	ds_write_b32 v42, v64
	s_waitcnt vmcnt(22)
	ds_write_b32 v44, v65
	s_waitcnt vmcnt(21)
	ds_write_b32 v46, v66
	s_waitcnt vmcnt(20)
	ds_write_b32 v48, v67
	s_waitcnt vmcnt(19)
	ds_write_b32 v50, v4
	s_waitcnt vmcnt(18)
	ds_write_b32 v52, v68
	s_waitcnt vmcnt(17)
	ds_write_b32 v54, v69
	s_waitcnt vmcnt(16)
	ds_write_b32 v56, v70
	s_waitcnt vmcnt(15)
	ds_write_b32 v126, v117
	s_waitcnt vmcnt(14)
	ds_write_b32 v128, v125
	s_waitcnt vmcnt(13)
	ds_write_b32 v130, v158
	s_waitcnt vmcnt(12)
	ds_write_b32 v132, v159
	s_waitcnt vmcnt(11)
	ds_write_b32 v134, v160
	s_waitcnt vmcnt(10)
	ds_write_b32 v136, v161
	s_waitcnt vmcnt(9)
	ds_write_b32 v138, v162
	s_waitcnt vmcnt(8)
	ds_write_b32 v140, v163
	s_waitcnt vmcnt(7)
	ds_write_b32 v142, v164
	s_waitcnt vmcnt(6)
	ds_write_b32 v144, v165
	s_waitcnt vmcnt(5)
	ds_write_b32 v146, v166
	s_waitcnt vmcnt(4)
	ds_write_b32 v148, v167
	s_waitcnt vmcnt(3)
	ds_write_b32 v150, v104
	s_waitcnt vmcnt(2)
	ds_write_b32 v152, v168
	s_waitcnt vmcnt(1)
	ds_write_b32 v154, v169
	s_waitcnt vmcnt(0)
	ds_write_b32 v156, v170
	s_waitcnt lgkmcnt(0)
	ds_read2_b32 v[18:19], v21 offset0:33 offset1:41
	ds_read2_b32 v[30:31], v21 offset1:8
	ds_read2_b32 v[32:33], v21 offset0:66 offset1:74
	ds_read2_b32 v[34:35], v21 offset0:99 offset1:107
	ds_read2_b32 v[36:37], v21 offset0:132 offset1:140
	ds_read2_b32 v[38:39], v21 offset0:165 offset1:173
	ds_read2_b32 v[40:41], v21 offset0:198 offset1:206
	ds_read2_b32 v[42:43], v21 offset0:231 offset1:239
	s_lshl_b32 s4, s7, 1
	v_or_b32_e32 v3, s6, v7
	v_lshl_add_u64 v[44:45], v[12:13], 0, s[4:5]
	v_lshlrev_b32_e32 v4, 11, v3
	s_waitcnt lgkmcnt(6)
	v_cvt_pk_bf16_f32 v26, v30, v18
	s_waitcnt lgkmcnt(4)
	v_cvt_pk_bf16_f32 v27, v32, v34
	s_waitcnt lgkmcnt(2)
	v_cvt_pk_bf16_f32 v28, v36, v38
	s_waitcnt lgkmcnt(0)
	v_cvt_pk_bf16_f32 v29, v40, v42
	v_lshl_add_u64 v[46:47], v[44:45], 0, v[4:5]
	global_store_dwordx4 v[46:47], v[26:29], off
	v_or_b32_e32 v3, s6, v22
	v_lshlrev_b32_e32 v4, 11, v3
	v_cvt_pk_bf16_f32 v26, v31, v19
	v_cvt_pk_bf16_f32 v27, v33, v35
	v_cvt_pk_bf16_f32 v28, v37, v39
	v_cvt_pk_bf16_f32 v29, v41, v43
	ds_read2_b32 v[30:31], v21 offset0:49 offset1:57
	ds_read2_b32 v[32:33], v21 offset0:16 offset1:24
	ds_read2_b32 v[34:35], v21 offset0:82 offset1:90
	ds_read2_b32 v[36:37], v21 offset0:115 offset1:123
	ds_read2_b32 v[38:39], v21 offset0:148 offset1:156
	ds_read2_b32 v[40:41], v21 offset0:181 offset1:189
	ds_read2_b32 v[42:43], v21 offset0:214 offset1:222
	ds_read2_b32 v[46:47], v21 offset0:247 offset1:255
	v_or_b32_e32 v3, s6, v23
	v_lshl_add_u64 v[18:19], v[44:45], 0, v[4:5]
	v_lshlrev_b32_e32 v4, 11, v3
	v_or_b32_e32 v3, s6, v24
	global_store_dwordx4 v[18:19], v[26:29], off
	v_lshl_add_u64 v[18:19], v[44:45], 0, v[4:5]
	v_lshlrev_b32_e32 v4, 11, v3
	s_waitcnt lgkmcnt(6)
	v_cvt_pk_bf16_f32 v26, v32, v30
	s_waitcnt lgkmcnt(4)
	v_cvt_pk_bf16_f32 v27, v34, v36
	s_waitcnt lgkmcnt(2)
	v_cvt_pk_bf16_f32 v28, v38, v40
	s_waitcnt lgkmcnt(0)
	v_cvt_pk_bf16_f32 v29, v42, v46
	global_store_dwordx4 v[18:19], v[26:29], off
	v_lshl_add_u64 v[18:19], v[44:45], 0, v[4:5]
	s_nop 0
	v_cvt_pk_bf16_f32 v26, v33, v31
	v_cvt_pk_bf16_f32 v27, v35, v37
	v_cvt_pk_bf16_f32 v28, v39, v41
	v_cvt_pk_bf16_f32 v29, v43, v47
	global_store_dwordx4 v[18:19], v[26:29], off
	s_waitcnt lgkmcnt(0)

.LBB0_55:
	s_lshl_b32 s13, s4, 1
	s_lshl_b32 s14, s7, 1
	v_or_b32_e32 v28, s14, v4
	s_add_i32 s15, s13, 4
	s_add_i32 s16, s14, 4
	s_add_i32 s17, s13, 8
	s_add_i32 s18, s14, 8
	s_add_i32 s19, s13, 12
	s_add_i32 s20, s14, 12
	s_add_i32 s21, s13, 16
	s_add_i32 s24, s14, 16
	s_add_i32 s25, s13, 20
	s_add_i32 s26, s14, 20
	s_add_i32 s27, s13, 24
	s_add_i32 s28, s14, 24
	s_add_i32 s29, s13, 28
	s_add_i32 s30, s14, 28
	v_or_b32_e32 v26, s13, v3
	v_ashrrev_i32_e32 v29, 31, v28
	v_or_b32_e32 v30, s15, v3
	v_or_b32_e32 v32, s16, v4
	v_or_b32_e32 v34, s17, v3
	v_or_b32_e32 v36, s18, v4
	v_or_b32_e32 v38, s19, v3
	v_or_b32_e32 v40, s20, v4
	v_or_b32_e32 v42, s21, v3
	v_or_b32_e32 v44, s24, v4
	v_or_b32_e32 v46, s25, v3
	v_or_b32_e32 v48, s26, v4
	v_or_b32_e32 v50, s27, v3
	v_or_b32_e32 v52, s28, v4
	v_or_b32_e32 v54, s29, v3
	v_or_b32_e32 v56, s30, v4
	v_ashrrev_i32_e32 v27, 31, v26
	v_lshlrev_b64 v[28:29], 15, v[28:29]
	v_ashrrev_i32_e32 v33, 31, v32
	v_ashrrev_i32_e32 v31, 31, v30
	v_ashrrev_i32_e32 v37, 31, v36
	v_ashrrev_i32_e32 v35, 31, v34
	v_ashrrev_i32_e32 v41, 31, v40
	v_ashrrev_i32_e32 v39, 31, v38
	v_ashrrev_i32_e32 v45, 31, v44
	v_ashrrev_i32_e32 v43, 31, v42
	v_ashrrev_i32_e32 v49, 31, v48
	v_ashrrev_i32_e32 v47, 31, v46
	v_ashrrev_i32_e32 v53, 31, v52
	v_ashrrev_i32_e32 v51, 31, v50
	v_ashrrev_i32_e32 v57, 31, v56
	v_ashrrev_i32_e32 v55, 31, v54
	v_lshlrev_b64 v[26:27], 15, v[26:27]
	v_lshl_add_u64 v[28:29], v[18:19], 0, v[28:29]
	v_lshlrev_b64 v[30:31], 15, v[30:31]
	v_lshlrev_b64 v[32:33], 15, v[32:33]
	v_lshlrev_b64 v[34:35], 15, v[34:35]
	v_lshlrev_b64 v[36:37], 15, v[36:37]
	v_lshlrev_b64 v[38:39], 15, v[38:39]
	v_lshlrev_b64 v[40:41], 15, v[40:41]
	v_lshlrev_b64 v[42:43], 15, v[42:43]
	v_lshlrev_b64 v[44:45], 15, v[44:45]
	v_lshlrev_b64 v[46:47], 15, v[46:47]
	v_lshlrev_b64 v[48:49], 15, v[48:49]
	v_lshlrev_b64 v[50:51], 15, v[50:51]
	v_lshlrev_b64 v[52:53], 15, v[52:53]
	v_lshlrev_b64 v[54:55], 15, v[54:55]
	v_lshlrev_b64 v[56:57], 15, v[56:57]
	v_lshl_add_u64 v[26:27], v[18:19], 0, v[26:27]
	v_lshl_add_u64 v[32:33], v[18:19], 0, v[32:33]
	v_lshl_add_u64 v[30:31], v[18:19], 0, v[30:31]
	v_lshl_add_u64 v[36:37], v[18:19], 0, v[36:37]
	v_lshl_add_u64 v[34:35], v[18:19], 0, v[34:35]
	v_lshl_add_u64 v[40:41], v[18:19], 0, v[40:41]
	v_lshl_add_u64 v[38:39], v[18:19], 0, v[38:39]
	v_lshl_add_u64 v[44:45], v[18:19], 0, v[44:45]
	v_lshl_add_u64 v[42:43], v[18:19], 0, v[42:43]
	v_lshl_add_u64 v[48:49], v[18:19], 0, v[48:49]
	v_lshl_add_u64 v[46:47], v[18:19], 0, v[46:47]
	v_lshl_add_u64 v[52:53], v[18:19], 0, v[52:53]
	v_lshl_add_u64 v[50:51], v[18:19], 0, v[50:51]
	v_lshl_add_u64 v[56:57], v[18:19], 0, v[56:57]
	v_lshl_add_u64 v[54:55], v[18:19], 0, v[54:55]
	global_load_dword v17, v[28:29], off
	global_load_dword v20, v[26:27], off
	global_load_dword v25, v[32:33], off
	global_load_dword v58, v[30:31], off
	global_load_dword v59, v[36:37], off
	global_load_dword v60, v[34:35], off
	global_load_dword v61, v[40:41], off
	global_load_dword v62, v[38:39], off
	global_load_dword v63, v[44:45], off
	global_load_dword v64, v[42:43], off
	global_load_dword v65, v[48:49], off
	global_load_dword v66, v[46:47], off
	global_load_dword v67, v[52:53], off
	global_load_dword v68, v[50:51], off
	global_load_dword v69, v[56:57], off
	global_load_dword v70, v[54:55], off
	v_or_b32_e32 v28, s13, v1
	v_or_b32_e32 v26, s14, v2
	s_add_i32 s7, s7, 16
	s_add_i32 s4, s4, 16
	s_add_i32 s9, s9, -16
	v_mad_u64_u32 v[26:27], s[22:23], v26, s12, v[6:7]
	v_mad_u64_u32 v[28:29], s[22:23], v28, s12, v[6:7]
	v_or_b32_e32 v27, s15, v1
	v_or_b32_e32 v29, s16, v2
	v_or_b32_e32 v36, s17, v1
	v_or_b32_e32 v34, s18, v2
	v_or_b32_e32 v40, s19, v1
	v_or_b32_e32 v38, s20, v2
	v_or_b32_e32 v44, s21, v1
	v_or_b32_e32 v42, s24, v2
	v_or_b32_e32 v48, s25, v1
	v_or_b32_e32 v46, s26, v2
	v_or_b32_e32 v52, s27, v1
	v_or_b32_e32 v50, s28, v2
	v_or_b32_e32 v56, s29, v1
	v_or_b32_e32 v54, s30, v2
	s_cmp_lg_u32 s9, 0
	v_mad_u64_u32 v[30:31], s[14:15], v29, s12, v[6:7]
	v_mad_u64_u32 v[32:33], s[14:15], v27, s12, v[6:7]
	v_mad_u64_u32 v[34:35], s[14:15], v34, s12, v[6:7]
	v_mad_u64_u32 v[36:37], s[14:15], v36, s12, v[6:7]
	v_mad_u64_u32 v[38:39], s[14:15], v38, s12, v[6:7]
	v_mad_u64_u32 v[40:41], s[14:15], v40, s12, v[6:7]
	v_mad_u64_u32 v[42:43], s[14:15], v42, s12, v[6:7]
	v_mad_u64_u32 v[44:45], s[14:15], v44, s12, v[6:7]
	v_mad_u64_u32 v[46:47], s[14:15], v46, s12, v[6:7]
	v_mad_u64_u32 v[48:49], s[14:15], v48, s12, v[6:7]
	v_mad_u64_u32 v[50:51], s[14:15], v50, s12, v[6:7]
	v_mad_u64_u32 v[52:53], s[14:15], v52, s12, v[6:7]
	v_mad_u64_u32 v[54:55], s[14:15], v54, s12, v[6:7]
	v_mad_u64_u32 v[56:57], s[14:15], v56, s12, v[6:7]
	s_lshl_b32 s13, s4, 1
	s_lshl_b32 s14, s7, 1
	v_or_b32_e32 v128, s14, v4
	s_add_i32 s15, s13, 4
	s_add_i32 s16, s14, 4
	s_add_i32 s17, s13, 8
	s_add_i32 s18, s14, 8
	s_add_i32 s19, s13, 12
	s_add_i32 s20, s14, 12
	s_add_i32 s21, s13, 16
	s_add_i32 s24, s14, 16
	s_add_i32 s25, s13, 20
	s_add_i32 s26, s14, 20
	s_add_i32 s27, s13, 24
	s_add_i32 s28, s14, 24
	s_add_i32 s29, s13, 28
	s_add_i32 s30, s14, 28
	v_or_b32_e32 v126, s13, v3
	v_ashrrev_i32_e32 v129, 31, v128
	v_or_b32_e32 v130, s15, v3
	v_or_b32_e32 v132, s16, v4
	v_or_b32_e32 v134, s17, v3
	v_or_b32_e32 v136, s18, v4
	v_or_b32_e32 v138, s19, v3
	v_or_b32_e32 v140, s20, v4
	v_or_b32_e32 v142, s21, v3
	v_or_b32_e32 v144, s24, v4
	v_or_b32_e32 v146, s25, v3
	v_or_b32_e32 v148, s26, v4
	v_or_b32_e32 v150, s27, v3
	v_or_b32_e32 v152, s28, v4
	v_or_b32_e32 v154, s29, v3
	v_or_b32_e32 v156, s30, v4
	v_ashrrev_i32_e32 v127, 31, v126
	v_lshlrev_b64 v[128:129], 15, v[128:129]
	v_ashrrev_i32_e32 v133, 31, v132
	v_ashrrev_i32_e32 v131, 31, v130
	v_ashrrev_i32_e32 v137, 31, v136
	v_ashrrev_i32_e32 v135, 31, v134
	v_ashrrev_i32_e32 v141, 31, v140
	v_ashrrev_i32_e32 v139, 31, v138
	v_ashrrev_i32_e32 v145, 31, v144
	v_ashrrev_i32_e32 v143, 31, v142
	v_ashrrev_i32_e32 v149, 31, v148
	v_ashrrev_i32_e32 v147, 31, v146
	v_ashrrev_i32_e32 v153, 31, v152
	v_ashrrev_i32_e32 v151, 31, v150
	v_ashrrev_i32_e32 v157, 31, v156
	v_ashrrev_i32_e32 v155, 31, v154
	v_lshlrev_b64 v[126:127], 15, v[126:127]
	v_lshl_add_u64 v[128:129], v[18:19], 0, v[128:129]
	v_lshlrev_b64 v[130:131], 15, v[130:131]
	v_lshlrev_b64 v[132:133], 15, v[132:133]
	v_lshlrev_b64 v[134:135], 15, v[134:135]
	v_lshlrev_b64 v[136:137], 15, v[136:137]
	v_lshlrev_b64 v[138:139], 15, v[138:139]
	v_lshlrev_b64 v[140:141], 15, v[140:141]
	v_lshlrev_b64 v[142:143], 15, v[142:143]
	v_lshlrev_b64 v[144:145], 15, v[144:145]
	v_lshlrev_b64 v[146:147], 15, v[146:147]
	v_lshlrev_b64 v[148:149], 15, v[148:149]
	v_lshlrev_b64 v[150:151], 15, v[150:151]
	v_lshlrev_b64 v[152:153], 15, v[152:153]
	v_lshlrev_b64 v[154:155], 15, v[154:155]
	v_lshlrev_b64 v[156:157], 15, v[156:157]
	v_lshl_add_u64 v[126:127], v[18:19], 0, v[126:127]
	v_lshl_add_u64 v[132:133], v[18:19], 0, v[132:133]
	v_lshl_add_u64 v[130:131], v[18:19], 0, v[130:131]
	v_lshl_add_u64 v[136:137], v[18:19], 0, v[136:137]
	v_lshl_add_u64 v[134:135], v[18:19], 0, v[134:135]
	v_lshl_add_u64 v[140:141], v[18:19], 0, v[140:141]
	v_lshl_add_u64 v[138:139], v[18:19], 0, v[138:139]
	v_lshl_add_u64 v[144:145], v[18:19], 0, v[144:145]
	v_lshl_add_u64 v[142:143], v[18:19], 0, v[142:143]
	v_lshl_add_u64 v[148:149], v[18:19], 0, v[148:149]
	v_lshl_add_u64 v[146:147], v[18:19], 0, v[146:147]
	v_lshl_add_u64 v[152:153], v[18:19], 0, v[152:153]
	v_lshl_add_u64 v[150:151], v[18:19], 0, v[150:151]
	v_lshl_add_u64 v[156:157], v[18:19], 0, v[156:157]
	v_lshl_add_u64 v[154:155], v[18:19], 0, v[154:155]
	global_load_dword v117, v[128:129], off
	global_load_dword v120, v[126:127], off
	global_load_dword v125, v[132:133], off
	global_load_dword v158, v[130:131], off
	global_load_dword v159, v[136:137], off
	global_load_dword v160, v[134:135], off
	global_load_dword v161, v[140:141], off
	global_load_dword v162, v[138:139], off
	global_load_dword v163, v[144:145], off
	global_load_dword v164, v[142:143], off
	global_load_dword v165, v[148:149], off
	global_load_dword v166, v[146:147], off
	global_load_dword v167, v[152:153], off
	global_load_dword v168, v[150:151], off
	global_load_dword v169, v[156:157], off
	global_load_dword v170, v[154:155], off
	v_or_b32_e32 v128, s13, v1
	v_or_b32_e32 v126, s14, v2
	s_add_i32 s7, s7, 16
	s_add_i32 s4, s4, 16
	s_add_i32 s9, s9, -16
	v_mad_u64_u32 v[126:127], s[22:23], v126, s12, v[6:7]
	v_mad_u64_u32 v[128:129], s[22:23], v128, s12, v[6:7]
	v_or_b32_e32 v127, s15, v1
	v_or_b32_e32 v129, s16, v2
	v_or_b32_e32 v136, s17, v1
	v_or_b32_e32 v134, s18, v2
	v_or_b32_e32 v140, s19, v1
	v_or_b32_e32 v138, s20, v2
	v_or_b32_e32 v144, s21, v1
	v_or_b32_e32 v142, s24, v2
	v_or_b32_e32 v148, s25, v1
	v_or_b32_e32 v146, s26, v2
	v_or_b32_e32 v152, s27, v1
	v_or_b32_e32 v150, s28, v2
	v_or_b32_e32 v156, s29, v1
	v_or_b32_e32 v154, s30, v2
	s_cmp_lg_u32 s9, 0
	v_mad_u64_u32 v[130:131], s[14:15], v129, s12, v[6:7]
	v_mad_u64_u32 v[132:133], s[14:15], v127, s12, v[6:7]
	v_mad_u64_u32 v[134:135], s[14:15], v134, s12, v[6:7]
	v_mad_u64_u32 v[136:137], s[14:15], v136, s12, v[6:7]
	v_mad_u64_u32 v[138:139], s[14:15], v138, s12, v[6:7]
	v_mad_u64_u32 v[140:141], s[14:15], v140, s12, v[6:7]
	v_mad_u64_u32 v[142:143], s[14:15], v142, s12, v[6:7]
	v_mad_u64_u32 v[144:145], s[14:15], v144, s12, v[6:7]
	v_mad_u64_u32 v[146:147], s[14:15], v146, s12, v[6:7]
	v_mad_u64_u32 v[148:149], s[14:15], v148, s12, v[6:7]
	v_mad_u64_u32 v[150:151], s[14:15], v150, s12, v[6:7]
	v_mad_u64_u32 v[152:153], s[14:15], v152, s12, v[6:7]
	v_mad_u64_u32 v[154:155], s[14:15], v154, s12, v[6:7]
	v_mad_u64_u32 v[156:157], s[14:15], v156, s12, v[6:7]
	s_waitcnt vmcnt(31)
	ds_write_b32 v26, v17
	s_waitcnt vmcnt(30)
	ds_write_b32 v28, v20
	s_waitcnt vmcnt(29)
	ds_write_b32 v30, v25
	s_waitcnt vmcnt(28)
	ds_write_b32 v32, v58
	s_waitcnt vmcnt(27)
	ds_write_b32 v34, v59
	s_waitcnt vmcnt(26)
	ds_write_b32 v36, v60
	s_waitcnt vmcnt(25)
	ds_write_b32 v38, v61
	s_waitcnt vmcnt(24)
	ds_write_b32 v40, v62
	s_waitcnt vmcnt(23)
	ds_write_b32 v42, v63
	s_waitcnt vmcnt(22)
	ds_write_b32 v44, v64
	s_waitcnt vmcnt(21)
	ds_write_b32 v46, v65
	s_waitcnt vmcnt(20)
	ds_write_b32 v48, v66
	s_waitcnt vmcnt(19)
	ds_write_b32 v50, v67
	s_waitcnt vmcnt(18)
	ds_write_b32 v52, v68
	s_waitcnt vmcnt(17)
	ds_write_b32 v54, v69
	s_waitcnt vmcnt(16)
	ds_write_b32 v56, v70
	s_waitcnt vmcnt(15)
	ds_write_b32 v126, v117
	s_waitcnt vmcnt(14)
	ds_write_b32 v128, v120
	s_waitcnt vmcnt(13)
	ds_write_b32 v130, v125
	s_waitcnt vmcnt(12)
	ds_write_b32 v132, v158
	s_waitcnt vmcnt(11)
	ds_write_b32 v134, v159
	s_waitcnt vmcnt(10)
	ds_write_b32 v136, v160
	s_waitcnt vmcnt(9)
	ds_write_b32 v138, v161
	s_waitcnt vmcnt(8)
	ds_write_b32 v140, v162
	s_waitcnt vmcnt(7)
	ds_write_b32 v142, v163
	s_waitcnt vmcnt(6)
	ds_write_b32 v144, v164
	s_waitcnt vmcnt(5)
	ds_write_b32 v146, v165
	s_waitcnt vmcnt(4)
	ds_write_b32 v148, v166
	s_waitcnt vmcnt(3)
	ds_write_b32 v150, v167
	s_waitcnt vmcnt(2)
	ds_write_b32 v152, v168
	s_waitcnt vmcnt(1)
	ds_write_b32 v154, v169
	s_waitcnt vmcnt(0)
	ds_write_b32 v156, v170
	s_waitcnt lgkmcnt(0)
	ds_read2_b32 v[18:19], v21 offset0:33 offset1:41
	ds_read2_b32 v[30:31], v21 offset1:8
	ds_read2_b32 v[32:33], v21 offset0:66 offset1:74
	ds_read2_b32 v[34:35], v21 offset0:99 offset1:107
	ds_read2_b32 v[36:37], v21 offset0:132 offset1:140
	ds_read2_b32 v[38:39], v21 offset0:165 offset1:173
	ds_read2_b32 v[40:41], v21 offset0:198 offset1:206
	ds_read2_b32 v[42:43], v21 offset0:231 offset1:239
	v_or_b32_e32 v46, s6, v7
	s_ashr_i32 s9, s8, 31
	v_ashrrev_i32_e32 v47, 31, v46
	v_lshl_add_u64 v[44:45], s[8:9], 1, v[14:15]
	v_lshlrev_b64 v[46:47], 11, v[46:47]
	s_waitcnt lgkmcnt(6)
	v_cvt_pk_bf16_f32 v26, v30, v18
	s_waitcnt lgkmcnt(4)
	v_cvt_pk_bf16_f32 v27, v32, v34
	s_waitcnt lgkmcnt(2)
	v_cvt_pk_bf16_f32 v28, v36, v38
	s_waitcnt lgkmcnt(0)
	v_cvt_pk_bf16_f32 v29, v40, v42
	v_lshl_add_u64 v[46:47], v[44:45], 0, v[46:47]
	v_or_b32_e32 v18, s6, v22
	global_store_dwordx4 v[46:47], v[26:29], off
	s_nop 1
	v_cvt_pk_bf16_f32 v26, v31, v19
	v_ashrrev_i32_e32 v19, 31, v18
	v_cvt_pk_bf16_f32 v27, v33, v35
	v_cvt_pk_bf16_f32 v28, v37, v39
	v_cvt_pk_bf16_f32 v29, v41, v43
	v_lshlrev_b64 v[18:19], 11, v[18:19]
	ds_read2_b32 v[30:31], v21 offset0:49 offset1:57
	ds_read2_b32 v[32:33], v21 offset0:16 offset1:24
	ds_read2_b32 v[34:35], v21 offset0:82 offset1:90
	ds_read2_b32 v[36:37], v21 offset0:115 offset1:123
	ds_read2_b32 v[38:39], v21 offset0:148 offset1:156
	ds_read2_b32 v[40:41], v21 offset0:181 offset1:189
	ds_read2_b32 v[42:43], v21 offset0:214 offset1:222
	ds_read2_b32 v[46:47], v21 offset0:247 offset1:255
	v_lshl_add_u64 v[18:19], v[44:45], 0, v[18:19]
	global_store_dwordx4 v[18:19], v[26:29], off
	v_or_b32_e32 v18, s6, v23
	v_ashrrev_i32_e32 v19, 31, v18
	v_lshlrev_b64 v[18:19], 11, v[18:19]
	s_waitcnt lgkmcnt(6)
	v_cvt_pk_bf16_f32 v26, v32, v30
	s_waitcnt lgkmcnt(4)
	v_cvt_pk_bf16_f32 v27, v34, v36
	s_waitcnt lgkmcnt(2)
	v_cvt_pk_bf16_f32 v28, v38, v40
	s_waitcnt lgkmcnt(0)
	v_cvt_pk_bf16_f32 v29, v42, v46
	v_lshl_add_u64 v[18:19], v[44:45], 0, v[18:19]
	global_store_dwordx4 v[18:19], v[26:29], off
	v_or_b32_e32 v18, s6, v24
	v_ashrrev_i32_e32 v19, 31, v18
	v_lshlrev_b64 v[18:19], 11, v[18:19]
	v_cvt_pk_bf16_f32 v26, v33, v31
	v_cvt_pk_bf16_f32 v27, v35, v37
	v_cvt_pk_bf16_f32 v28, v39, v41
	v_cvt_pk_bf16_f32 v29, v43, v47
	v_lshl_add_u64 v[18:19], v[44:45], 0, v[18:19]
	global_store_dwordx4 v[18:19], v[26:29], off
	s_waitcnt lgkmcnt(0)
	s_branch .LBB0_36
